# v48 = v43 + rwkv_post loop unrolled by two with a renamed register set (loads of two trips issued back to back, then both computed)
# baseline (speedup 1.0000x reference)
.LBB0_765:
	s_mov_b32 s0, 1
	s_cmp_ge_i32 s34, s0
	s_mov_b64 s[0:1], -1
	s_cbranch_scc1 .LBB0_764
	v_mov_b32_e32 v4, v5
	v_mov_b32_e32 v0, v5
	s_nop 0
	v_mbcnt_lo_u32_b32 v0, -1, v0
	v_mbcnt_hi_u32_b32 v0, -1, v0
	v_add_u32_e32 v0, s33, v0
	v_ashrrev_i32_e32 v0, 4, v0
	v_and_b32_e32 v0, -4, v0
	v_add_u32_e32 v22, s21, v0
	v_cmp_gt_i32_e32 vcc, s35, v22
	s_and_saveexec_b64 s[24:25], vcc
	s_cbranch_execz .LBB0_763
	global_load_dwordx4 v[0:3], v5, s[12:13]
	v_mbcnt_lo_u32_b32 v4, -1, v4
	v_mbcnt_hi_u32_b32 v4, -1, v4
	v_and_b32_e32 v10, 63, v4
	v_or_b32_e32 v12, 64, v10
	v_or_b32_e32 v14, 0x80, v10
	v_or_b32_e32 v16, 0xc0, v10
	v_lshlrev_b32_e32 v4, 1, v10
	v_lshl_add_u64 v[6:7], s[8:9], 0, v[4:5]
	v_lshl_add_u64 v[8:9], s[14:15], 0, v[4:5]
	s_mov_b64 s[26:27], 0
	v_lshlrev_b32_e32 v4, 2, v10
	v_lshlrev_b32_e32 v10, 2, v12
	v_lshlrev_b32_e32 v12, 2, v14
	v_lshlrev_b32_e32 v14, 2, v16
	v_mov_b32_e32 v132, v4
	v_mov_b32_e32 v133, v5
	v_mov_b32_e32 v134, v6
	v_mov_b32_e32 v135, v7
	v_mov_b32_e32 v136, v8
	v_mov_b32_e32 v137, v9
	v_mov_b32_e32 v138, v10
	v_mov_b32_e32 v140, v12
	v_mov_b32_e32 v142, v14
.LBB0_768:
	v_ashrrev_i32_e32 v18, 2, v22
	v_mov_b64_e32 v[20:21], s[30:31]
	s_waitcnt vmcnt(0)
	v_readfirstlane_b32 s1, v1
	v_readfirstlane_b32 s0, v0
	v_add_u32_e32 v22, s23, v22
	v_ashrrev_i32_e32 v19, 31, v18
	v_mad_i64_i32 v[20:21], s[4:5], v18, s36, v[20:21]
	v_mov_b32_e32 v11, v5
	v_mov_b32_e32 v13, v5
	v_mov_b32_e32 v15, v5
	v_readfirstlane_b32 s3, v3
	v_readfirstlane_b32 s2, v2
	v_lshl_add_u64 v[24:25], s[0:1], 0, v[4:5]
	v_cmp_lt_i32_e32 vcc, s40, v22
	v_lshl_add_u64 v[28:29], v[20:21], 0, s[16:17]
	v_lshl_add_u64 v[30:31], v[18:19], 4, s[10:11]
	v_lshl_add_u64 v[26:27], s[2:3], 0, v[4:5]
	v_lshl_add_u64 v[20:21], v[20:21], 0, s[18:19]
	v_lshlrev_b64 v[32:33], 9, v[18:19]
	v_lshlrev_b64 v[18:19], 11, v[18:19]
	global_load_dword v23, v[24:25], off
	global_load_dword v50, v[24:25], off offset:256
	global_load_dword v51, v[24:25], off offset:512
	global_load_dword v52, v[24:25], off offset:768
	global_load_dword v53, v[26:27], off
	global_load_dword v54, v[26:27], off offset:256
	global_load_dword v55, v[26:27], off offset:512
	global_load_dword v56, v[26:27], off offset:768
	s_or_b64 s[26:27], vcc, s[26:27]
	v_lshl_add_u64 v[24:25], v[28:29], 0, v[4:5]
	v_add_co_u32_e32 v36, vcc, s37, v30
	v_lshl_add_u64 v[40:41], v[28:29], 0, v[10:11]
	v_lshl_add_u64 v[44:45], v[28:29], 0, v[12:13]
	v_lshl_add_u64 v[28:29], v[28:29], 0, v[14:15]
	v_lshl_add_u64 v[34:35], v[20:21], 0, v[4:5]
	v_addc_co_u32_e32 v37, vcc, 0, v31, vcc
	v_lshl_add_u64 v[32:33], v[6:7], 0, v[32:33]
	v_lshl_add_u64 v[38:39], v[8:9], 0, v[18:19]
	v_lshl_add_u64 v[42:43], v[20:21], 0, v[10:11]
	v_lshl_add_u64 v[46:47], v[20:21], 0, v[12:13]
	v_lshl_add_u64 v[48:49], v[20:21], 0, v[14:15]
	global_load_dword v11, v[24:25], off
	global_load_dword v13, v[34:35], off
	global_load_dwordx4 v[18:21], v[30:31], off
	s_nop 0
	global_load_dwordx4 v[24:27], v[36:37], off
	global_load_ushort v15, v[32:33], off
	global_load_ushort v57, v[38:39], off offset:512
	global_load_dword v58, v[40:41], off
	global_load_dword v59, v[42:43], off
	global_load_ushort v60, v[32:33], off offset:128
	global_load_ushort v61, v[38:39], off offset:640
	global_load_dword v62, v[44:45], off
	global_load_dword v63, v[46:47], off
	global_load_ushort v64, v[32:33], off offset:256
	global_load_ushort v65, v[38:39], off offset:768
	global_load_dword v66, v[28:29], off
	global_load_dword v67, v[48:49], off
	s_nop 0
	global_load_ushort v28, v[38:39], off offset:896
	global_load_ushort v29, v[32:33], off offset:384
	v_mov_b64_e32 v[16:17], s[22:23]
	s_mov_b64 s[52:53], exec
	s_andn2_b64 exec, exec, s[26:27]
	s_nop 4
	v_ashrrev_i32_e32 v146, 2, v22
	v_mov_b64_e32 v[148:149], s[30:31]
	v_readfirstlane_b32 s1, v1
	v_readfirstlane_b32 s0, v0
	v_add_u32_e32 v22, s23, v22
	v_ashrrev_i32_e32 v147, 31, v146
	v_mad_i64_i32 v[148:149], s[4:5], v146, s36, v[148:149]
	v_mov_b32_e32 v139, v133
	v_mov_b32_e32 v141, v133
	v_mov_b32_e32 v143, v133
	v_readfirstlane_b32 s3, v3
	v_readfirstlane_b32 s2, v2
	v_lshl_add_u64 v[152:153], s[0:1], 0, v[132:133]
	v_cmp_lt_i32_e32 vcc, s40, v22
	v_lshl_add_u64 v[156:157], v[148:149], 0, s[16:17]
	v_lshl_add_u64 v[158:159], v[146:147], 4, s[10:11]
	v_lshl_add_u64 v[154:155], s[2:3], 0, v[132:133]
	v_lshl_add_u64 v[148:149], v[148:149], 0, s[18:19]
	v_lshlrev_b64 v[160:161], 9, v[146:147]
	v_lshlrev_b64 v[146:147], 11, v[146:147]
	global_load_dword v151, v[152:153], off
	global_load_dword v178, v[152:153], off offset:256
	global_load_dword v179, v[152:153], off offset:512
	global_load_dword v180, v[152:153], off offset:768
	global_load_dword v181, v[154:155], off
	global_load_dword v182, v[154:155], off offset:256
	global_load_dword v183, v[154:155], off offset:512
	global_load_dword v184, v[154:155], off offset:768
	s_or_b64 s[26:27], vcc, s[26:27]
	v_lshl_add_u64 v[152:153], v[156:157], 0, v[132:133]
	v_add_co_u32_e32 v164, vcc, s37, v158
	v_lshl_add_u64 v[168:169], v[156:157], 0, v[138:139]
	v_lshl_add_u64 v[172:173], v[156:157], 0, v[140:141]
	v_lshl_add_u64 v[156:157], v[156:157], 0, v[142:143]
	v_lshl_add_u64 v[162:163], v[148:149], 0, v[132:133]
	v_addc_co_u32_e32 v165, vcc, 0, v159, vcc
	v_lshl_add_u64 v[160:161], v[134:135], 0, v[160:161]
	v_lshl_add_u64 v[166:167], v[136:137], 0, v[146:147]
	v_lshl_add_u64 v[170:171], v[148:149], 0, v[138:139]
	v_lshl_add_u64 v[174:175], v[148:149], 0, v[140:141]
	v_lshl_add_u64 v[176:177], v[148:149], 0, v[142:143]
	global_load_dword v139, v[152:153], off
	global_load_dword v141, v[162:163], off
	global_load_dwordx4 v[146:149], v[158:159], off
	s_nop 0
	global_load_dwordx4 v[152:155], v[164:165], off
	global_load_ushort v143, v[160:161], off
	global_load_ushort v185, v[166:167], off offset:512
	global_load_dword v186, v[168:169], off
	global_load_dword v187, v[170:171], off
	global_load_ushort v188, v[160:161], off offset:128
	global_load_ushort v189, v[166:167], off offset:640
	global_load_dword v190, v[172:173], off
	global_load_dword v191, v[174:175], off
	global_load_ushort v192, v[160:161], off offset:256
	global_load_ushort v193, v[166:167], off offset:768
	global_load_dword v194, v[156:157], off
	global_load_dword v195, v[176:177], off
	s_nop 0
	global_load_ushort v156, v[166:167], off offset:896
	global_load_ushort v157, v[160:161], off offset:384
	v_mov_b64_e32 v[144:145], s[22:23]
	s_mov_b64 s[54:55], exec
	s_mov_b64 exec, s[52:53]
	s_nop 4
	s_waitcnt vmcnt(0)
	v_add_f32_e32 v11, v11, v13
	v_add_f32_e32 v13, v18, v24
	v_add_f32_e32 v32, v19, v25
	v_add_f32_dpp v18, v11, v11 quad_perm:[1,0,3,2] row_mask:0xf bank_mask:0xf bound_ctrl:1
	v_add_f32_e32 v36, v20, v26
	v_add_f32_e32 v31, v58, v59
	v_add_f32_e32 v42, v21, v27
	v_add_f32_dpp v18, v18, v18 quad_perm:[2,3,0,1] row_mask:0xf bank_mask:0xf bound_ctrl:1
	v_add_f32_dpp v19, v31, v31 quad_perm:[1,0,3,2] row_mask:0xf bank_mask:0xf bound_ctrl:1
	v_add_f32_e32 v35, v62, v63
	v_add_f32_dpp v18, v18, v18 row_half_mirror row_mask:0xf bank_mask:0xf bound_ctrl:1
	v_add_f32_dpp v19, v19, v19 quad_perm:[2,3,0,1] row_mask:0xf bank_mask:0xf bound_ctrl:1
	v_add_f32_dpp v20, v35, v35 quad_perm:[1,0,3,2] row_mask:0xf bank_mask:0xf bound_ctrl:1
	v_add_f32_e32 v41, v66, v67
	v_add_f32_dpp v19, v19, v19 row_half_mirror row_mask:0xf bank_mask:0xf bound_ctrl:1
	v_add_f32_dpp v20, v20, v20 quad_perm:[2,3,0,1] row_mask:0xf bank_mask:0xf bound_ctrl:1
	v_add_f32_dpp v21, v41, v41 quad_perm:[1,0,3,2] row_mask:0xf bank_mask:0xf bound_ctrl:1
	v_add_f32_dpp v18, v18, v18 row_mirror row_mask:0xf bank_mask:0xf bound_ctrl:1
	v_add_f32_dpp v20, v20, v20 row_half_mirror row_mask:0xf bank_mask:0xf bound_ctrl:1
	v_add_f32_dpp v21, v21, v21 quad_perm:[2,3,0,1] row_mask:0xf bank_mask:0xf bound_ctrl:1
	v_add_f32_dpp v19, v19, v19 row_mirror row_mask:0xf bank_mask:0xf bound_ctrl:1
	v_add_f32_dpp v20, v20, v20 row_mirror row_mask:0xf bank_mask:0xf bound_ctrl:1
	v_add_f32_dpp v21, v21, v21 row_half_mirror row_mask:0xf bank_mask:0xf bound_ctrl:1
	v_readlane_b32 s41, v18, 16
	v_readlane_b32 s44, v18, 48
	v_add_f32_dpp v21, v21, v21 row_mirror row_mask:0xf bank_mask:0xf bound_ctrl:1
	v_readlane_b32 s45, v19, 16
	v_readlane_b32 s46, v19, 48
	v_readlane_b32 s0, v18, 0
	v_readlane_b32 s1, v18, 32
	v_readlane_b32 s2, v19, 0
	v_readlane_b32 s3, v19, 32
	v_readlane_b32 s4, v20, 0
	v_readlane_b32 s47, v20, 16
	v_readlane_b32 s5, v20, 32
	v_readlane_b32 s48, v20, 48
	v_readlane_b32 s42, v21, 0
	v_readlane_b32 s49, v21, 16
	v_readlane_b32 s43, v21, 32
	v_readlane_b32 s50, v21, 48
	v_mov_b32_e32 v18, s41
	v_mov_b32_e32 v19, s44
	v_mov_b32_e32 v20, s45
	v_mov_b32_e32 v21, s46
	v_mov_b32_e32 v24, s47
	v_mov_b32_e32 v25, s48
	v_mov_b32_e32 v26, s49
	v_mov_b32_e32 v27, s50
	v_pk_add_f32 v[18:19], s[0:1], v[18:19]
	v_pk_add_f32 v[20:21], s[2:3], v[20:21]
	v_pk_add_f32 v[24:25], s[4:5], v[24:25]
	v_pk_add_f32 v[26:27], s[42:43], v[26:27]
	v_add_f32_e32 v18, v18, v19
	v_add_f32_e32 v19, v20, v21
	v_add_f32_e32 v20, v24, v25
	v_add_f32_e32 v21, v26, v27
	v_fmac_f32_e32 v11, 0xbc800000, v18
	v_fmac_f32_e32 v31, 0xbc800000, v19
	v_fmac_f32_e32 v35, 0xbc800000, v20
	v_fmac_f32_e32 v41, 0xbc800000, v21
	v_mul_f32_e32 v18, v11, v11
	v_mul_f32_e32 v19, v31, v31
	v_mul_f32_e32 v20, v35, v35
	v_mul_f32_e32 v21, v41, v41
	v_mov_b32_dpp v18, v18 quad_perm:[1,0,3,2] row_mask:0xf bank_mask:0xf bound_ctrl:1
	v_mov_b32_dpp v19, v19 quad_perm:[1,0,3,2] row_mask:0xf bank_mask:0xf bound_ctrl:1
	v_mov_b32_dpp v20, v20 quad_perm:[1,0,3,2] row_mask:0xf bank_mask:0xf bound_ctrl:1
	v_mov_b32_dpp v21, v21 quad_perm:[1,0,3,2] row_mask:0xf bank_mask:0xf bound_ctrl:1
	v_fmac_f32_e32 v18, v11, v11
	v_fmac_f32_e32 v19, v31, v31
	v_fmac_f32_e32 v20, v35, v35
	v_fmac_f32_e32 v21, v41, v41
	v_add_f32_dpp v18, v18, v18 quad_perm:[2,3,0,1] row_mask:0xf bank_mask:0xf bound_ctrl:1
	v_add_f32_dpp v19, v19, v19 quad_perm:[2,3,0,1] row_mask:0xf bank_mask:0xf bound_ctrl:1
	v_add_f32_dpp v20, v20, v20 quad_perm:[2,3,0,1] row_mask:0xf bank_mask:0xf bound_ctrl:1
	v_add_f32_dpp v21, v21, v21 quad_perm:[2,3,0,1] row_mask:0xf bank_mask:0xf bound_ctrl:1
	v_add_f32_dpp v18, v18, v18 row_half_mirror row_mask:0xf bank_mask:0xf bound_ctrl:1
	v_add_f32_dpp v19, v19, v19 row_half_mirror row_mask:0xf bank_mask:0xf bound_ctrl:1
	v_add_f32_dpp v20, v20, v20 row_half_mirror row_mask:0xf bank_mask:0xf bound_ctrl:1
	v_add_f32_dpp v21, v21, v21 row_half_mirror row_mask:0xf bank_mask:0xf bound_ctrl:1
	v_add_f32_dpp v18, v18, v18 row_mirror row_mask:0xf bank_mask:0xf bound_ctrl:1
	v_add_f32_dpp v19, v19, v19 row_mirror row_mask:0xf bank_mask:0xf bound_ctrl:1
	v_add_f32_dpp v20, v20, v20 row_mirror row_mask:0xf bank_mask:0xf bound_ctrl:1
	v_add_f32_dpp v21, v21, v21 row_mirror row_mask:0xf bank_mask:0xf bound_ctrl:1
	v_readlane_b32 s41, v18, 16
	v_readlane_b32 s44, v18, 48
	v_readlane_b32 s45, v19, 16
	v_readlane_b32 s46, v19, 48
	v_readlane_b32 s0, v18, 0
	v_readlane_b32 s1, v18, 32
	v_readlane_b32 s2, v19, 0
	v_readlane_b32 s3, v19, 32
	v_readlane_b32 s4, v20, 0
	v_readlane_b32 s47, v20, 16
	v_readlane_b32 s5, v20, 32
	v_readlane_b32 s48, v20, 48
	v_readlane_b32 s42, v21, 0
	v_readlane_b32 s49, v21, 16
	v_readlane_b32 s43, v21, 32
	v_readlane_b32 s50, v21, 48
	v_mov_b32_e32 v18, s41
	v_mov_b32_e32 v19, s44
	v_mov_b32_e32 v20, s45
	v_mov_b32_e32 v21, s46
	v_mov_b32_e32 v24, s47
	v_mov_b32_e32 v25, s48
	v_mov_b32_e32 v26, s49
	v_mov_b32_e32 v27, s50
	v_pk_add_f32 v[18:19], s[0:1], v[18:19]
	v_pk_add_f32 v[20:21], s[2:3], v[20:21]
	v_lshlrev_b32_e32 v43, 16, v29
	v_lshlrev_b32_e32 v44, 16, v28
	v_pk_add_f32 v[24:25], s[4:5], v[24:25]
	v_pk_add_f32 v[26:27], s[42:43], v[26:27]
	v_mov_b32_e32 v28, v20
	v_mov_b32_e32 v29, v18
	v_mov_b32_e32 v18, v21
	v_mov_b32_e32 v20, v26
	v_mov_b32_e32 v21, v24
	v_mov_b32_e32 v24, v27
	v_pk_add_f32 v[18:19], v[28:29], v[18:19]
	v_pk_add_f32 v[20:21], v[20:21], v[24:25]
	v_pk_fma_f32 v[18:19], v[18:19], s[20:21], v[16:17] op_sel_hi:[1,0,0]
	v_pk_fma_f32 v[16:17], v[20:21], s[20:21], v[16:17] op_sel_hi:[1,0,0]
	v_mul_f32_e32 v20, 0x4b800000, v19
	v_cmp_gt_f32_e64 s[4:5], s38, v19
	v_mul_f32_e32 v21, 0x4b800000, v18
	v_cmp_gt_f32_e32 vcc, s38, v18
	v_mul_f32_e32 v24, 0x4b800000, v17
	v_mul_f32_e32 v25, 0x4b800000, v16
	v_cmp_gt_f32_e64 s[0:1], s38, v16
	v_cmp_gt_f32_e64 s[2:3], s38, v17
	v_cndmask_b32_e64 v19, v19, v20, s[4:5]
	v_cndmask_b32_e32 v18, v18, v21, vcc
	v_cndmask_b32_e64 v17, v17, v24, s[2:3]
	v_cndmask_b32_e64 v16, v16, v25, s[0:1]
	v_rsq_f32_e32 v19, v19
	v_rsq_f32_e32 v18, v18
	v_rsq_f32_e32 v17, v17
	v_rsq_f32_e32 v16, v16
	v_mul_f32_e32 v20, 0x45800000, v19
	v_mul_f32_e32 v21, 0x45800000, v18
	v_mul_f32_e32 v24, 0x45800000, v17
	v_mul_f32_e32 v25, 0x45800000, v16
	v_cndmask_b32_e64 v19, v19, v20, s[4:5]
	v_cndmask_b32_e32 v18, v18, v21, vcc
	v_cndmask_b32_e64 v17, v17, v24, s[2:3]
	v_cndmask_b32_e64 v16, v16, v25, s[0:1]
	v_mul_f32_e32 v11, v11, v19
	v_lshlrev_b32_e32 v15, 16, v15
	v_mul_f32_e32 v18, v31, v18
	v_mul_f32_e32 v17, v35, v17
	v_mul_f32_e32 v16, v41, v16
	s_waitcnt lgkmcnt(0)
	v_fmac_f32_e32 v53, v23, v11
	v_lshlrev_b32_e32 v30, 16, v57
	v_lshlrev_b32_e32 v33, 16, v60
	v_lshlrev_b32_e32 v37, 16, v64
	v_fmac_f32_e32 v54, v50, v18
	v_fmac_f32_e32 v55, v51, v17
	v_fmac_f32_e32 v56, v52, v16
	v_fmac_f32_e32 v53, v13, v15
	v_lshlrev_b32_e32 v34, 16, v61
	v_lshlrev_b32_e32 v40, 16, v65
	v_fmac_f32_e32 v54, v32, v33
	v_fmac_f32_e32 v55, v36, v37
	v_fmac_f32_e32 v56, v42, v43
	v_mul_f32_e32 v11, v53, v30
	v_mul_f32_e32 v13, v54, v34
	v_mul_f32_e32 v15, v55, v40
	v_mul_f32_e32 v16, v56, v44
	v_bfe_u32 v17, v11, 16, 1
	v_bfe_u32 v18, v13, 16, 1
	v_bfe_u32 v19, v15, 16, 1
	v_bfe_u32 v20, v16, 16, 1
	v_add3_u32 v11, v11, v17, s39
	v_add3_u32 v13, v13, v18, s39
	v_add3_u32 v15, v15, v19, s39
	v_add3_u32 v16, v16, v20, s39
	global_store_short_d16_hi v[38:39], v11, off offset:512
	global_store_short_d16_hi v[38:39], v13, off offset:640
	global_store_short_d16_hi v[38:39], v15, off offset:768
	global_store_short_d16_hi v[38:39], v16, off offset:896
	s_mov_b64 exec, s[54:55]
	s_nop 4
	s_waitcnt vmcnt(0)
	v_add_f32_e32 v139, v139, v141
	v_add_f32_e32 v141, v146, v152
	v_add_f32_e32 v160, v147, v153
	v_add_f32_dpp v146, v139, v139 quad_perm:[1,0,3,2] row_mask:0xf bank_mask:0xf bound_ctrl:1
	v_add_f32_e32 v164, v148, v154
	v_add_f32_e32 v159, v186, v187
	v_add_f32_e32 v170, v149, v155
	v_add_f32_dpp v146, v146, v146 quad_perm:[2,3,0,1] row_mask:0xf bank_mask:0xf bound_ctrl:1
	v_add_f32_dpp v147, v159, v159 quad_perm:[1,0,3,2] row_mask:0xf bank_mask:0xf bound_ctrl:1
	v_add_f32_e32 v163, v190, v191
	v_add_f32_dpp v146, v146, v146 row_half_mirror row_mask:0xf bank_mask:0xf bound_ctrl:1
	v_add_f32_dpp v147, v147, v147 quad_perm:[2,3,0,1] row_mask:0xf bank_mask:0xf bound_ctrl:1
	v_add_f32_dpp v148, v163, v163 quad_perm:[1,0,3,2] row_mask:0xf bank_mask:0xf bound_ctrl:1
	v_add_f32_e32 v169, v194, v195
	v_add_f32_dpp v147, v147, v147 row_half_mirror row_mask:0xf bank_mask:0xf bound_ctrl:1
	v_add_f32_dpp v148, v148, v148 quad_perm:[2,3,0,1] row_mask:0xf bank_mask:0xf bound_ctrl:1
	v_add_f32_dpp v149, v169, v169 quad_perm:[1,0,3,2] row_mask:0xf bank_mask:0xf bound_ctrl:1
	v_add_f32_dpp v146, v146, v146 row_mirror row_mask:0xf bank_mask:0xf bound_ctrl:1
	v_add_f32_dpp v148, v148, v148 row_half_mirror row_mask:0xf bank_mask:0xf bound_ctrl:1
	v_add_f32_dpp v149, v149, v149 quad_perm:[2,3,0,1] row_mask:0xf bank_mask:0xf bound_ctrl:1
	v_add_f32_dpp v147, v147, v147 row_mirror row_mask:0xf bank_mask:0xf bound_ctrl:1
	v_add_f32_dpp v148, v148, v148 row_mirror row_mask:0xf bank_mask:0xf bound_ctrl:1
	v_add_f32_dpp v149, v149, v149 row_half_mirror row_mask:0xf bank_mask:0xf bound_ctrl:1
	v_readlane_b32 s41, v146, 16
	v_readlane_b32 s44, v146, 48
	v_add_f32_dpp v149, v149, v149 row_mirror row_mask:0xf bank_mask:0xf bound_ctrl:1
	v_readlane_b32 s45, v147, 16
	v_readlane_b32 s46, v147, 48
	v_readlane_b32 s0, v146, 0
	v_readlane_b32 s1, v146, 32
	v_readlane_b32 s2, v147, 0
	v_readlane_b32 s3, v147, 32
	v_readlane_b32 s4, v148, 0
	v_readlane_b32 s47, v148, 16
	v_readlane_b32 s5, v148, 32
	v_readlane_b32 s48, v148, 48
	v_readlane_b32 s42, v149, 0
	v_readlane_b32 s49, v149, 16
	v_readlane_b32 s43, v149, 32
	v_readlane_b32 s50, v149, 48
	v_mov_b32_e32 v146, s41
	v_mov_b32_e32 v147, s44
	v_mov_b32_e32 v148, s45
	v_mov_b32_e32 v149, s46
	v_mov_b32_e32 v152, s47
	v_mov_b32_e32 v153, s48
	v_mov_b32_e32 v154, s49
	v_mov_b32_e32 v155, s50
	v_pk_add_f32 v[146:147], s[0:1], v[146:147]
	v_pk_add_f32 v[148:149], s[2:3], v[148:149]
	v_pk_add_f32 v[152:153], s[4:5], v[152:153]
	v_pk_add_f32 v[154:155], s[42:43], v[154:155]
	v_add_f32_e32 v146, v146, v147
	v_add_f32_e32 v147, v148, v149
	v_add_f32_e32 v148, v152, v153
	v_add_f32_e32 v149, v154, v155
	v_fmac_f32_e32 v139, 0xbc800000, v146
	v_fmac_f32_e32 v159, 0xbc800000, v147
	v_fmac_f32_e32 v163, 0xbc800000, v148
	v_fmac_f32_e32 v169, 0xbc800000, v149
	v_mul_f32_e32 v146, v139, v139
	v_mul_f32_e32 v147, v159, v159
	v_mul_f32_e32 v148, v163, v163
	v_mul_f32_e32 v149, v169, v169
	v_mov_b32_dpp v146, v146 quad_perm:[1,0,3,2] row_mask:0xf bank_mask:0xf bound_ctrl:1
	v_mov_b32_dpp v147, v147 quad_perm:[1,0,3,2] row_mask:0xf bank_mask:0xf bound_ctrl:1
	v_mov_b32_dpp v148, v148 quad_perm:[1,0,3,2] row_mask:0xf bank_mask:0xf bound_ctrl:1
	v_mov_b32_dpp v149, v149 quad_perm:[1,0,3,2] row_mask:0xf bank_mask:0xf bound_ctrl:1
	v_fmac_f32_e32 v146, v139, v139
	v_fmac_f32_e32 v147, v159, v159
	v_fmac_f32_e32 v148, v163, v163
	v_fmac_f32_e32 v149, v169, v169
	v_add_f32_dpp v146, v146, v146 quad_perm:[2,3,0,1] row_mask:0xf bank_mask:0xf bound_ctrl:1
	v_add_f32_dpp v147, v147, v147 quad_perm:[2,3,0,1] row_mask:0xf bank_mask:0xf bound_ctrl:1
	v_add_f32_dpp v148, v148, v148 quad_perm:[2,3,0,1] row_mask:0xf bank_mask:0xf bound_ctrl:1
	v_add_f32_dpp v149, v149, v149 quad_perm:[2,3,0,1] row_mask:0xf bank_mask:0xf bound_ctrl:1
	v_add_f32_dpp v146, v146, v146 row_half_mirror row_mask:0xf bank_mask:0xf bound_ctrl:1
	v_add_f32_dpp v147, v147, v147 row_half_mirror row_mask:0xf bank_mask:0xf bound_ctrl:1
	v_add_f32_dpp v148, v148, v148 row_half_mirror row_mask:0xf bank_mask:0xf bound_ctrl:1
	v_add_f32_dpp v149, v149, v149 row_half_mirror row_mask:0xf bank_mask:0xf bound_ctrl:1
	v_add_f32_dpp v146, v146, v146 row_mirror row_mask:0xf bank_mask:0xf bound_ctrl:1
	v_add_f32_dpp v147, v147, v147 row_mirror row_mask:0xf bank_mask:0xf bound_ctrl:1
	v_add_f32_dpp v148, v148, v148 row_mirror row_mask:0xf bank_mask:0xf bound_ctrl:1
	v_add_f32_dpp v149, v149, v149 row_mirror row_mask:0xf bank_mask:0xf bound_ctrl:1
	v_readlane_b32 s41, v146, 16
	v_readlane_b32 s44, v146, 48
	v_readlane_b32 s45, v147, 16
	v_readlane_b32 s46, v147, 48
	v_readlane_b32 s0, v146, 0
	v_readlane_b32 s1, v146, 32
	v_readlane_b32 s2, v147, 0
	v_readlane_b32 s3, v147, 32
	v_readlane_b32 s4, v148, 0
	v_readlane_b32 s47, v148, 16
	v_readlane_b32 s5, v148, 32
	v_readlane_b32 s48, v148, 48
	v_readlane_b32 s42, v149, 0
	v_readlane_b32 s49, v149, 16
	v_readlane_b32 s43, v149, 32
	v_readlane_b32 s50, v149, 48
	v_mov_b32_e32 v146, s41
	v_mov_b32_e32 v147, s44
	v_mov_b32_e32 v148, s45
	v_mov_b32_e32 v149, s46
	v_mov_b32_e32 v152, s47
	v_mov_b32_e32 v153, s48
	v_mov_b32_e32 v154, s49
	v_mov_b32_e32 v155, s50
	v_pk_add_f32 v[146:147], s[0:1], v[146:147]
	v_pk_add_f32 v[148:149], s[2:3], v[148:149]
	v_lshlrev_b32_e32 v171, 16, v157
	v_lshlrev_b32_e32 v172, 16, v156
	v_pk_add_f32 v[152:153], s[4:5], v[152:153]
	v_pk_add_f32 v[154:155], s[42:43], v[154:155]
	v_mov_b32_e32 v156, v148
	v_mov_b32_e32 v157, v146
	v_mov_b32_e32 v146, v149
	v_mov_b32_e32 v148, v154
	v_mov_b32_e32 v149, v152
	v_mov_b32_e32 v152, v155
	v_pk_add_f32 v[146:147], v[156:157], v[146:147]
	v_pk_add_f32 v[148:149], v[148:149], v[152:153]
	v_pk_fma_f32 v[146:147], v[146:147], s[20:21], v[144:145] op_sel_hi:[1,0,0]
	v_pk_fma_f32 v[144:145], v[148:149], s[20:21], v[144:145] op_sel_hi:[1,0,0]
	v_mul_f32_e32 v148, 0x4b800000, v147
	v_cmp_gt_f32_e64 s[4:5], s38, v147
	v_mul_f32_e32 v149, 0x4b800000, v146
	v_cmp_gt_f32_e32 vcc, s38, v146
	v_mul_f32_e32 v152, 0x4b800000, v145
	v_mul_f32_e32 v153, 0x4b800000, v144
	v_cmp_gt_f32_e64 s[0:1], s38, v144
	v_cmp_gt_f32_e64 s[2:3], s38, v145
	v_cndmask_b32_e64 v147, v147, v148, s[4:5]
	v_cndmask_b32_e32 v146, v146, v149, vcc
	v_cndmask_b32_e64 v145, v145, v152, s[2:3]
	v_cndmask_b32_e64 v144, v144, v153, s[0:1]
	v_rsq_f32_e32 v147, v147
	v_rsq_f32_e32 v146, v146
	v_rsq_f32_e32 v145, v145
	v_rsq_f32_e32 v144, v144
	v_mul_f32_e32 v148, 0x45800000, v147
	v_mul_f32_e32 v149, 0x45800000, v146
	v_mul_f32_e32 v152, 0x45800000, v145
	v_mul_f32_e32 v153, 0x45800000, v144
	v_cndmask_b32_e64 v147, v147, v148, s[4:5]
	v_cndmask_b32_e32 v146, v146, v149, vcc
	v_cndmask_b32_e64 v145, v145, v152, s[2:3]
	v_cndmask_b32_e64 v144, v144, v153, s[0:1]
	v_mul_f32_e32 v139, v139, v147
	v_lshlrev_b32_e32 v143, 16, v143
	v_mul_f32_e32 v146, v159, v146
	v_mul_f32_e32 v145, v163, v145
	v_mul_f32_e32 v144, v169, v144
	s_waitcnt lgkmcnt(0)
	v_fmac_f32_e32 v181, v151, v139
	v_lshlrev_b32_e32 v158, 16, v185
	v_lshlrev_b32_e32 v161, 16, v188
	v_lshlrev_b32_e32 v165, 16, v192
	v_fmac_f32_e32 v182, v178, v146
	v_fmac_f32_e32 v183, v179, v145
	v_fmac_f32_e32 v184, v180, v144
	v_fmac_f32_e32 v181, v141, v143
	v_lshlrev_b32_e32 v162, 16, v189
	v_lshlrev_b32_e32 v168, 16, v193
	v_fmac_f32_e32 v182, v160, v161
	v_fmac_f32_e32 v183, v164, v165
	v_fmac_f32_e32 v184, v170, v171
	v_mul_f32_e32 v139, v181, v158
	v_mul_f32_e32 v141, v182, v162
	v_mul_f32_e32 v143, v183, v168
	v_mul_f32_e32 v144, v184, v172
	v_bfe_u32 v145, v139, 16, 1
	v_bfe_u32 v146, v141, 16, 1
	v_bfe_u32 v147, v143, 16, 1
	v_bfe_u32 v148, v144, 16, 1
	v_add3_u32 v139, v139, v145, s39
	v_add3_u32 v141, v141, v146, s39
	v_add3_u32 v143, v143, v147, s39
	v_add3_u32 v144, v144, v148, s39
	global_store_short_d16_hi v[166:167], v139, off offset:512
	global_store_short_d16_hi v[166:167], v141, off offset:640
	global_store_short_d16_hi v[166:167], v143, off offset:768
	global_store_short_d16_hi v[166:167], v144, off offset:896
	s_mov_b64 exec, s[52:53]
	s_nop 4
	s_andn2_b64 exec, exec, s[26:27]
	s_cbranch_execnz .LBB0_768
	s_branch .LBB0_763

.LBB0_1745:
	s_mov_b32 s0, 1
	s_cmp_ge_i32 s34, s0
	s_mov_b64 s[0:1], -1
	s_cbranch_scc1 .LBB0_1744
	v_mov_b32_e32 v4, v5
	v_mov_b32_e32 v0, v5
	s_nop 0
	v_mbcnt_lo_u32_b32 v0, -1, v0
	v_mbcnt_hi_u32_b32 v0, -1, v0
	v_add_u32_e32 v0, s33, v0
	v_ashrrev_i32_e32 v0, 4, v0
	v_and_b32_e32 v0, -4, v0
	v_add_u32_e32 v20, s21, v0
	v_cmp_gt_i32_e32 vcc, s35, v20
	s_and_saveexec_b64 s[24:25], vcc
	s_cbranch_execz .LBB0_1743
	global_load_dwordx4 v[0:3], v5, s[12:13]
	v_mbcnt_lo_u32_b32 v4, -1, v4
	v_mbcnt_hi_u32_b32 v4, -1, v4
	v_and_b32_e32 v10, 63, v4
	v_or_b32_e32 v12, 64, v10
	v_or_b32_e32 v14, 0x80, v10
	v_or_b32_e32 v16, 0xc0, v10
	v_lshlrev_b32_e32 v4, 1, v10
	v_lshl_add_u64 v[6:7], s[8:9], 0, v[4:5]
	v_lshl_add_u64 v[8:9], s[14:15], 0, v[4:5]
	s_mov_b64 s[26:27], 0
	v_lshlrev_b32_e32 v4, 2, v10
	v_lshlrev_b32_e32 v10, 2, v12
	v_lshlrev_b32_e32 v12, 2, v14
	v_lshlrev_b32_e32 v14, 2, v16
	v_mov_b32_e32 v132, v4
	v_mov_b32_e32 v133, v5
	v_mov_b32_e32 v134, v6
	v_mov_b32_e32 v135, v7
	v_mov_b32_e32 v136, v8
	v_mov_b32_e32 v137, v9
	v_mov_b32_e32 v138, v10
	v_mov_b32_e32 v140, v12
	v_mov_b32_e32 v142, v14
.LBB0_1748:
	v_ashrrev_i32_e32 v22, 31, v20
	v_ashrrev_i32_e32 v21, 2, v20
	s_waitcnt vmcnt(0)
	v_readfirstlane_b32 s1, v1
	v_readfirstlane_b32 s0, v0
	v_lshrrev_b32_e32 v26, 21, v22
	v_readfirstlane_b32 s3, v3
	v_readfirstlane_b32 s2, v2
	v_lshl_add_u64 v[22:23], s[0:1], 0, v[4:5]
	v_add_u32_e32 v26, v21, v26
	v_lshl_add_u64 v[24:25], s[2:3], 0, v[4:5]
	global_load_dword v50, v[22:23], off offset:1024
	global_load_dword v51, v[22:23], off offset:1280
	global_load_dword v52, v[22:23], off offset:1536
	global_load_dword v53, v[22:23], off offset:1792
	global_load_dword v54, v[24:25], off offset:1024
	global_load_dword v55, v[24:25], off offset:1280
	global_load_dword v56, v[24:25], off offset:1536
	global_load_dword v57, v[24:25], off offset:1792
	v_ashrrev_i32_e32 v22, 11, v26
	v_lshlrev_b32_e32 v22, 8, v22
	v_mov_b64_e32 v[18:19], s[30:31]
	v_add3_u32 v22, v21, v22, s36
	v_add_u32_e32 v20, s23, v20
	v_ashrrev_i32_e32 v23, 31, v22
	v_mad_i64_i32 v[18:19], s[0:1], v22, s37, v[18:19]
	v_mov_b32_e32 v11, v5
	v_mov_b32_e32 v13, v5
	v_mov_b32_e32 v15, v5
	v_cmp_lt_i32_e32 vcc, s41, v20
	v_lshl_add_u64 v[24:25], v[18:19], 0, s[16:17]
	v_lshl_add_u64 v[18:19], v[18:19], 0, s[18:19]
	v_lshl_add_u64 v[30:31], v[22:23], 4, s[10:11]
	s_or_b64 s[26:27], vcc, s[26:27]
	v_lshlrev_b64 v[26:27], 9, v[22:23]
	v_lshlrev_b64 v[22:23], 11, v[22:23]
	v_lshl_add_u64 v[28:29], v[24:25], 0, v[4:5]
	v_lshl_add_u64 v[32:33], v[18:19], 0, v[4:5]
	v_add_co_u32_e32 v34, vcc, s38, v30
	v_lshl_add_u64 v[42:43], v[18:19], 0, v[10:11]
	v_lshl_add_u64 v[46:47], v[18:19], 0, v[12:13]
	v_lshl_add_u64 v[18:19], v[18:19], 0, v[14:15]
	v_addc_co_u32_e32 v35, vcc, 0, v31, vcc
	v_lshl_add_u64 v[36:37], v[6:7], 0, v[26:27]
	v_lshl_add_u64 v[38:39], v[8:9], 0, v[22:23]
	v_lshl_add_u64 v[40:41], v[24:25], 0, v[10:11]
	v_lshl_add_u64 v[44:45], v[24:25], 0, v[12:13]
	v_lshl_add_u64 v[48:49], v[24:25], 0, v[14:15]
	global_load_dword v11, v[28:29], off
	global_load_dword v13, v[32:33], off
	global_load_dwordx4 v[22:25], v[30:31], off
	s_nop 0
	global_load_dwordx4 v[26:29], v[34:35], off
	global_load_ushort v15, v[36:37], off
	global_load_ushort v21, v[38:39], off offset:512
	global_load_dword v58, v[40:41], off
	global_load_dword v59, v[42:43], off
	global_load_ushort v60, v[36:37], off offset:128
	global_load_ushort v61, v[38:39], off offset:640
	global_load_dword v62, v[44:45], off
	global_load_dword v63, v[46:47], off
	global_load_ushort v64, v[36:37], off offset:256
	global_load_ushort v65, v[38:39], off offset:768
	global_load_dword v66, v[48:49], off
	global_load_dword v67, v[18:19], off
	s_nop 0
	global_load_ushort v18, v[38:39], off offset:896
	global_load_ushort v19, v[36:37], off offset:384
	v_mov_b64_e32 v[16:17], s[22:23]
	s_mov_b64 s[52:53], exec
	s_andn2_b64 exec, exec, s[26:27]
	s_nop 4
	v_ashrrev_i32_e32 v150, 31, v20
	v_ashrrev_i32_e32 v149, 2, v20
	v_readfirstlane_b32 s1, v1
	v_readfirstlane_b32 s0, v0
	v_lshrrev_b32_e32 v154, 21, v150
	v_readfirstlane_b32 s3, v3
	v_readfirstlane_b32 s2, v2
	v_lshl_add_u64 v[150:151], s[0:1], 0, v[132:133]
	v_add_u32_e32 v154, v149, v154
	v_lshl_add_u64 v[152:153], s[2:3], 0, v[132:133]
	global_load_dword v178, v[150:151], off offset:1024
	global_load_dword v179, v[150:151], off offset:1280
	global_load_dword v180, v[150:151], off offset:1536
	global_load_dword v181, v[150:151], off offset:1792
	global_load_dword v182, v[152:153], off offset:1024
	global_load_dword v183, v[152:153], off offset:1280
	global_load_dword v184, v[152:153], off offset:1536
	global_load_dword v185, v[152:153], off offset:1792
	v_ashrrev_i32_e32 v150, 11, v154
	v_lshlrev_b32_e32 v150, 8, v150
	v_mov_b64_e32 v[146:147], s[30:31]
	v_add3_u32 v150, v149, v150, s36
	v_add_u32_e32 v20, s23, v20
	v_ashrrev_i32_e32 v151, 31, v150
	v_mad_i64_i32 v[146:147], s[0:1], v150, s37, v[146:147]
	v_mov_b32_e32 v139, v133
	v_mov_b32_e32 v141, v133
	v_mov_b32_e32 v143, v133
	v_cmp_lt_i32_e32 vcc, s41, v20
	v_lshl_add_u64 v[152:153], v[146:147], 0, s[16:17]
	v_lshl_add_u64 v[146:147], v[146:147], 0, s[18:19]
	v_lshl_add_u64 v[158:159], v[150:151], 4, s[10:11]
	s_or_b64 s[26:27], vcc, s[26:27]
	v_lshlrev_b64 v[154:155], 9, v[150:151]
	v_lshlrev_b64 v[150:151], 11, v[150:151]
	v_lshl_add_u64 v[156:157], v[152:153], 0, v[132:133]
	v_lshl_add_u64 v[160:161], v[146:147], 0, v[132:133]
	v_add_co_u32_e32 v162, vcc, s38, v158
	v_lshl_add_u64 v[170:171], v[146:147], 0, v[138:139]
	v_lshl_add_u64 v[174:175], v[146:147], 0, v[140:141]
	v_lshl_add_u64 v[146:147], v[146:147], 0, v[142:143]
	v_addc_co_u32_e32 v163, vcc, 0, v159, vcc
	v_lshl_add_u64 v[164:165], v[134:135], 0, v[154:155]
	v_lshl_add_u64 v[166:167], v[136:137], 0, v[150:151]
	v_lshl_add_u64 v[168:169], v[152:153], 0, v[138:139]
	v_lshl_add_u64 v[172:173], v[152:153], 0, v[140:141]
	v_lshl_add_u64 v[176:177], v[152:153], 0, v[142:143]
	global_load_dword v139, v[156:157], off
	global_load_dword v141, v[160:161], off
	global_load_dwordx4 v[150:153], v[158:159], off
	s_nop 0
	global_load_dwordx4 v[154:157], v[162:163], off
	global_load_ushort v143, v[164:165], off
	global_load_ushort v149, v[166:167], off offset:512
	global_load_dword v186, v[168:169], off
	global_load_dword v187, v[170:171], off
	global_load_ushort v188, v[164:165], off offset:128
	global_load_ushort v189, v[166:167], off offset:640
	global_load_dword v190, v[172:173], off
	global_load_dword v191, v[174:175], off
	global_load_ushort v192, v[164:165], off offset:256
	global_load_ushort v193, v[166:167], off offset:768
	global_load_dword v194, v[176:177], off
	global_load_dword v195, v[146:147], off
	s_nop 0
	global_load_ushort v146, v[166:167], off offset:896
	global_load_ushort v147, v[164:165], off offset:384
	v_mov_b64_e32 v[144:145], s[22:23]
	s_mov_b64 s[54:55], exec
	s_mov_b64 exec, s[52:53]
	s_nop 4
	s_waitcnt vmcnt(0)
	v_add_f32_e32 v11, v11, v13
	v_add_f32_e32 v13, v22, v26
	v_add_f32_e32 v31, v23, v27
	v_add_f32_e32 v35, v24, v28
	v_add_f32_e32 v41, v25, v29
	v_add_f32_e32 v30, v58, v59
	v_lshlrev_b32_e32 v15, 16, v15
	v_lshlrev_b32_e32 v21, 16, v21
	v_lshlrev_b32_e32 v32, 16, v60
	v_add_f32_e32 v34, v62, v63
	v_lshlrev_b32_e32 v36, 16, v64
	v_lshlrev_b32_e32 v33, 16, v61
	v_add_f32_dpp v22, v34, v34 quad_perm:[1,0,3,2] row_mask:0xf bank_mask:0xf bound_ctrl:1
	v_add_f32_e32 v40, v66, v67
	v_lshlrev_b32_e32 v37, 16, v65
	v_add_f32_dpp v22, v22, v22 quad_perm:[2,3,0,1] row_mask:0xf bank_mask:0xf bound_ctrl:1
	v_add_f32_dpp v23, v40, v40 quad_perm:[1,0,3,2] row_mask:0xf bank_mask:0xf bound_ctrl:1
	v_lshlrev_b32_e32 v43, 16, v18
	v_lshlrev_b32_e32 v42, 16, v19
	v_add_f32_dpp v18, v11, v11 quad_perm:[1,0,3,2] row_mask:0xf bank_mask:0xf bound_ctrl:1
	v_add_f32_dpp v19, v30, v30 quad_perm:[1,0,3,2] row_mask:0xf bank_mask:0xf bound_ctrl:1
	v_add_f32_dpp v23, v23, v23 quad_perm:[2,3,0,1] row_mask:0xf bank_mask:0xf bound_ctrl:1
	v_add_f32_dpp v18, v18, v18 quad_perm:[2,3,0,1] row_mask:0xf bank_mask:0xf bound_ctrl:1
	v_add_f32_dpp v19, v19, v19 quad_perm:[2,3,0,1] row_mask:0xf bank_mask:0xf bound_ctrl:1
	v_add_f32_dpp v22, v22, v22 row_half_mirror row_mask:0xf bank_mask:0xf bound_ctrl:1
	v_add_f32_dpp v18, v18, v18 row_half_mirror row_mask:0xf bank_mask:0xf bound_ctrl:1
	v_add_f32_dpp v19, v19, v19 row_half_mirror row_mask:0xf bank_mask:0xf bound_ctrl:1
	v_add_f32_dpp v23, v23, v23 row_half_mirror row_mask:0xf bank_mask:0xf bound_ctrl:1
	v_add_f32_dpp v18, v18, v18 row_mirror row_mask:0xf bank_mask:0xf bound_ctrl:1
	v_add_f32_dpp v19, v19, v19 row_mirror row_mask:0xf bank_mask:0xf bound_ctrl:1
	v_add_f32_dpp v22, v22, v22 row_mirror row_mask:0xf bank_mask:0xf bound_ctrl:1
	v_add_f32_dpp v23, v23, v23 row_mirror row_mask:0xf bank_mask:0xf bound_ctrl:1
	v_readlane_b32 s44, v18, 16
	v_readlane_b32 s45, v18, 48
	v_readlane_b32 s46, v19, 16
	v_readlane_b32 s47, v19, 48
	v_readlane_b32 s0, v18, 0
	v_readlane_b32 s1, v18, 32
	v_readlane_b32 s2, v19, 0
	v_readlane_b32 s3, v19, 32
	v_readlane_b32 s4, v22, 0
	v_readlane_b32 s48, v22, 16
	v_readlane_b32 s5, v22, 32
	v_readlane_b32 s49, v22, 48
	v_readlane_b32 s42, v23, 0
	v_readlane_b32 s50, v23, 16
	v_readlane_b32 s43, v23, 32
	v_readlane_b32 s51, v23, 48
	v_mov_b32_e32 v18, s44
	v_mov_b32_e32 v19, s45
	v_mov_b32_e32 v22, s46
	v_mov_b32_e32 v23, s47
	v_mov_b32_e32 v24, s48
	v_mov_b32_e32 v25, s49
	v_mov_b32_e32 v26, s50
	v_mov_b32_e32 v27, s51
	v_pk_add_f32 v[18:19], s[0:1], v[18:19]
	v_pk_add_f32 v[22:23], s[2:3], v[22:23]
	v_pk_add_f32 v[24:25], s[4:5], v[24:25]
	v_pk_add_f32 v[26:27], s[42:43], v[26:27]
	v_add_f32_e32 v18, v18, v19
	v_add_f32_e32 v19, v22, v23
	v_add_f32_e32 v22, v24, v25
	v_add_f32_e32 v23, v26, v27
	v_fmac_f32_e32 v11, 0xbc800000, v18
	v_fmac_f32_e32 v30, 0xbc800000, v19
	v_fmac_f32_e32 v34, 0xbc800000, v22
	v_fmac_f32_e32 v40, 0xbc800000, v23
	v_mul_f32_e32 v18, v11, v11
	v_mul_f32_e32 v19, v30, v30
	v_mul_f32_e32 v22, v34, v34
	v_mul_f32_e32 v23, v40, v40
	v_mov_b32_dpp v18, v18 quad_perm:[1,0,3,2] row_mask:0xf bank_mask:0xf bound_ctrl:1
	v_mov_b32_dpp v19, v19 quad_perm:[1,0,3,2] row_mask:0xf bank_mask:0xf bound_ctrl:1
	v_mov_b32_dpp v22, v22 quad_perm:[1,0,3,2] row_mask:0xf bank_mask:0xf bound_ctrl:1
	v_mov_b32_dpp v23, v23 quad_perm:[1,0,3,2] row_mask:0xf bank_mask:0xf bound_ctrl:1
	v_fmac_f32_e32 v18, v11, v11
	v_fmac_f32_e32 v19, v30, v30
	v_fmac_f32_e32 v22, v34, v34
	v_fmac_f32_e32 v23, v40, v40
	v_add_f32_dpp v18, v18, v18 quad_perm:[2,3,0,1] row_mask:0xf bank_mask:0xf bound_ctrl:1
	v_add_f32_dpp v19, v19, v19 quad_perm:[2,3,0,1] row_mask:0xf bank_mask:0xf bound_ctrl:1
	v_add_f32_dpp v22, v22, v22 quad_perm:[2,3,0,1] row_mask:0xf bank_mask:0xf bound_ctrl:1
	v_add_f32_dpp v23, v23, v23 quad_perm:[2,3,0,1] row_mask:0xf bank_mask:0xf bound_ctrl:1
	v_add_f32_dpp v18, v18, v18 row_half_mirror row_mask:0xf bank_mask:0xf bound_ctrl:1
	v_add_f32_dpp v19, v19, v19 row_half_mirror row_mask:0xf bank_mask:0xf bound_ctrl:1
	v_add_f32_dpp v22, v22, v22 row_half_mirror row_mask:0xf bank_mask:0xf bound_ctrl:1
	v_add_f32_dpp v23, v23, v23 row_half_mirror row_mask:0xf bank_mask:0xf bound_ctrl:1
	v_add_f32_dpp v18, v18, v18 row_mirror row_mask:0xf bank_mask:0xf bound_ctrl:1
	v_add_f32_dpp v19, v19, v19 row_mirror row_mask:0xf bank_mask:0xf bound_ctrl:1
	v_add_f32_dpp v22, v22, v22 row_mirror row_mask:0xf bank_mask:0xf bound_ctrl:1
	v_add_f32_dpp v23, v23, v23 row_mirror row_mask:0xf bank_mask:0xf bound_ctrl:1
	v_readlane_b32 s44, v18, 16
	v_readlane_b32 s45, v18, 48
	v_readlane_b32 s46, v19, 16
	v_readlane_b32 s47, v19, 48
	v_readlane_b32 s0, v18, 0
	v_readlane_b32 s1, v18, 32
	v_readlane_b32 s2, v19, 0
	v_readlane_b32 s3, v19, 32
	v_readlane_b32 s4, v22, 0
	v_readlane_b32 s48, v22, 16
	v_readlane_b32 s5, v22, 32
	v_readlane_b32 s49, v22, 48
	v_readlane_b32 s42, v23, 0
	v_readlane_b32 s50, v23, 16
	v_readlane_b32 s43, v23, 32
	v_readlane_b32 s51, v23, 48
	v_mov_b32_e32 v18, s44
	v_mov_b32_e32 v19, s45
	v_mov_b32_e32 v22, s46
	v_mov_b32_e32 v23, s47
	v_mov_b32_e32 v24, s48
	v_mov_b32_e32 v25, s49
	v_mov_b32_e32 v26, s50
	v_mov_b32_e32 v27, s51
	v_pk_add_f32 v[18:19], s[0:1], v[18:19]
	v_pk_add_f32 v[22:23], s[2:3], v[22:23]
	v_pk_add_f32 v[24:25], s[4:5], v[24:25]
	v_pk_add_f32 v[26:27], s[42:43], v[26:27]
	v_mov_b32_e32 v28, v22
	v_mov_b32_e32 v29, v18
	v_mov_b32_e32 v18, v23
	v_mov_b32_e32 v22, v26
	v_mov_b32_e32 v23, v24
	v_mov_b32_e32 v24, v27
	v_pk_add_f32 v[18:19], v[28:29], v[18:19]
	v_pk_add_f32 v[22:23], v[22:23], v[24:25]
	v_pk_fma_f32 v[18:19], v[18:19], s[20:21], v[16:17] op_sel_hi:[1,0,0]
	v_pk_fma_f32 v[16:17], v[22:23], s[20:21], v[16:17] op_sel_hi:[1,0,0]
	v_mul_f32_e32 v22, 0x4b800000, v19
	v_cmp_gt_f32_e64 s[4:5], s39, v19
	v_mul_f32_e32 v23, 0x4b800000, v18
	v_cmp_gt_f32_e32 vcc, s39, v18
	v_mul_f32_e32 v24, 0x4b800000, v17
	v_mul_f32_e32 v25, 0x4b800000, v16
	v_cmp_gt_f32_e64 s[0:1], s39, v16
	v_cmp_gt_f32_e64 s[2:3], s39, v17
	v_cndmask_b32_e64 v19, v19, v22, s[4:5]
	v_cndmask_b32_e32 v18, v18, v23, vcc
	v_cndmask_b32_e64 v17, v17, v24, s[2:3]
	v_cndmask_b32_e64 v16, v16, v25, s[0:1]
	v_rsq_f32_e32 v19, v19
	v_rsq_f32_e32 v18, v18
	v_rsq_f32_e32 v17, v17
	v_rsq_f32_e32 v16, v16
	v_mul_f32_e32 v22, 0x45800000, v19
	v_mul_f32_e32 v23, 0x45800000, v18
	v_mul_f32_e32 v24, 0x45800000, v17
	v_mul_f32_e32 v25, 0x45800000, v16
	v_cndmask_b32_e64 v19, v19, v22, s[4:5]
	v_cndmask_b32_e32 v18, v18, v23, vcc
	v_cndmask_b32_e64 v17, v17, v24, s[2:3]
	v_cndmask_b32_e64 v16, v16, v25, s[0:1]
	v_mul_f32_e32 v11, v11, v19
	v_mul_f32_e32 v18, v30, v18
	v_mul_f32_e32 v17, v34, v17
	v_mul_f32_e32 v16, v40, v16
	s_waitcnt lgkmcnt(0)
	v_fmac_f32_e32 v54, v50, v11
	v_fmac_f32_e32 v55, v51, v18
	v_fmac_f32_e32 v56, v52, v17
	v_fmac_f32_e32 v57, v53, v16
	v_fmac_f32_e32 v54, v13, v15
	v_fmac_f32_e32 v55, v31, v32
	v_fmac_f32_e32 v56, v35, v36
	v_fmac_f32_e32 v57, v41, v42
	v_mul_f32_e32 v11, v54, v21
	v_mul_f32_e32 v13, v55, v33
	v_mul_f32_e32 v15, v56, v37
	v_mul_f32_e32 v16, v57, v43
	v_bfe_u32 v17, v11, 16, 1
	v_bfe_u32 v18, v13, 16, 1
	v_bfe_u32 v19, v15, 16, 1
	v_bfe_u32 v21, v16, 16, 1
	v_add3_u32 v11, v11, v17, s40
	v_add3_u32 v13, v13, v18, s40
	v_add3_u32 v15, v15, v19, s40
	v_add3_u32 v16, v16, v21, s40
	global_store_short_d16_hi v[38:39], v11, off offset:512
	global_store_short_d16_hi v[38:39], v13, off offset:640
	global_store_short_d16_hi v[38:39], v15, off offset:768
	global_store_short_d16_hi v[38:39], v16, off offset:896
	s_mov_b64 exec, s[54:55]
	s_nop 4
	s_waitcnt vmcnt(0)
	v_add_f32_e32 v139, v139, v141
	v_add_f32_e32 v141, v150, v154
	v_add_f32_e32 v159, v151, v155
	v_add_f32_e32 v163, v152, v156
	v_add_f32_e32 v169, v153, v157
	v_add_f32_e32 v158, v186, v187
	v_lshlrev_b32_e32 v143, 16, v143
	v_lshlrev_b32_e32 v149, 16, v149
	v_lshlrev_b32_e32 v160, 16, v188
	v_add_f32_e32 v162, v190, v191
	v_lshlrev_b32_e32 v164, 16, v192
	v_lshlrev_b32_e32 v161, 16, v189
	v_add_f32_dpp v150, v162, v162 quad_perm:[1,0,3,2] row_mask:0xf bank_mask:0xf bound_ctrl:1
	v_add_f32_e32 v168, v194, v195
	v_lshlrev_b32_e32 v165, 16, v193
	v_add_f32_dpp v150, v150, v150 quad_perm:[2,3,0,1] row_mask:0xf bank_mask:0xf bound_ctrl:1
	v_add_f32_dpp v151, v168, v168 quad_perm:[1,0,3,2] row_mask:0xf bank_mask:0xf bound_ctrl:1
	v_lshlrev_b32_e32 v171, 16, v146
	v_lshlrev_b32_e32 v170, 16, v147
	v_add_f32_dpp v146, v139, v139 quad_perm:[1,0,3,2] row_mask:0xf bank_mask:0xf bound_ctrl:1
	v_add_f32_dpp v147, v158, v158 quad_perm:[1,0,3,2] row_mask:0xf bank_mask:0xf bound_ctrl:1
	v_add_f32_dpp v151, v151, v151 quad_perm:[2,3,0,1] row_mask:0xf bank_mask:0xf bound_ctrl:1
	v_add_f32_dpp v146, v146, v146 quad_perm:[2,3,0,1] row_mask:0xf bank_mask:0xf bound_ctrl:1
	v_add_f32_dpp v147, v147, v147 quad_perm:[2,3,0,1] row_mask:0xf bank_mask:0xf bound_ctrl:1
	v_add_f32_dpp v150, v150, v150 row_half_mirror row_mask:0xf bank_mask:0xf bound_ctrl:1
	v_add_f32_dpp v146, v146, v146 row_half_mirror row_mask:0xf bank_mask:0xf bound_ctrl:1
	v_add_f32_dpp v147, v147, v147 row_half_mirror row_mask:0xf bank_mask:0xf bound_ctrl:1
	v_add_f32_dpp v151, v151, v151 row_half_mirror row_mask:0xf bank_mask:0xf bound_ctrl:1
	v_add_f32_dpp v146, v146, v146 row_mirror row_mask:0xf bank_mask:0xf bound_ctrl:1
	v_add_f32_dpp v147, v147, v147 row_mirror row_mask:0xf bank_mask:0xf bound_ctrl:1
	v_add_f32_dpp v150, v150, v150 row_mirror row_mask:0xf bank_mask:0xf bound_ctrl:1
	v_add_f32_dpp v151, v151, v151 row_mirror row_mask:0xf bank_mask:0xf bound_ctrl:1
	v_readlane_b32 s44, v146, 16
	v_readlane_b32 s45, v146, 48
	v_readlane_b32 s46, v147, 16
	v_readlane_b32 s47, v147, 48
	v_readlane_b32 s0, v146, 0
	v_readlane_b32 s1, v146, 32
	v_readlane_b32 s2, v147, 0
	v_readlane_b32 s3, v147, 32
	v_readlane_b32 s4, v150, 0
	v_readlane_b32 s48, v150, 16
	v_readlane_b32 s5, v150, 32
	v_readlane_b32 s49, v150, 48
	v_readlane_b32 s42, v151, 0
	v_readlane_b32 s50, v151, 16
	v_readlane_b32 s43, v151, 32
	v_readlane_b32 s51, v151, 48
	v_mov_b32_e32 v146, s44
	v_mov_b32_e32 v147, s45
	v_mov_b32_e32 v150, s46
	v_mov_b32_e32 v151, s47
	v_mov_b32_e32 v152, s48
	v_mov_b32_e32 v153, s49
	v_mov_b32_e32 v154, s50
	v_mov_b32_e32 v155, s51
	v_pk_add_f32 v[146:147], s[0:1], v[146:147]
	v_pk_add_f32 v[150:151], s[2:3], v[150:151]
	v_pk_add_f32 v[152:153], s[4:5], v[152:153]
	v_pk_add_f32 v[154:155], s[42:43], v[154:155]
	v_add_f32_e32 v146, v146, v147
	v_add_f32_e32 v147, v150, v151
	v_add_f32_e32 v150, v152, v153
	v_add_f32_e32 v151, v154, v155
	v_fmac_f32_e32 v139, 0xbc800000, v146
	v_fmac_f32_e32 v158, 0xbc800000, v147
	v_fmac_f32_e32 v162, 0xbc800000, v150
	v_fmac_f32_e32 v168, 0xbc800000, v151
	v_mul_f32_e32 v146, v139, v139
	v_mul_f32_e32 v147, v158, v158
	v_mul_f32_e32 v150, v162, v162
	v_mul_f32_e32 v151, v168, v168
	v_mov_b32_dpp v146, v146 quad_perm:[1,0,3,2] row_mask:0xf bank_mask:0xf bound_ctrl:1
	v_mov_b32_dpp v147, v147 quad_perm:[1,0,3,2] row_mask:0xf bank_mask:0xf bound_ctrl:1
	v_mov_b32_dpp v150, v150 quad_perm:[1,0,3,2] row_mask:0xf bank_mask:0xf bound_ctrl:1
	v_mov_b32_dpp v151, v151 quad_perm:[1,0,3,2] row_mask:0xf bank_mask:0xf bound_ctrl:1
	v_fmac_f32_e32 v146, v139, v139
	v_fmac_f32_e32 v147, v158, v158
	v_fmac_f32_e32 v150, v162, v162
	v_fmac_f32_e32 v151, v168, v168
	v_add_f32_dpp v146, v146, v146 quad_perm:[2,3,0,1] row_mask:0xf bank_mask:0xf bound_ctrl:1
	v_add_f32_dpp v147, v147, v147 quad_perm:[2,3,0,1] row_mask:0xf bank_mask:0xf bound_ctrl:1
	v_add_f32_dpp v150, v150, v150 quad_perm:[2,3,0,1] row_mask:0xf bank_mask:0xf bound_ctrl:1
	v_add_f32_dpp v151, v151, v151 quad_perm:[2,3,0,1] row_mask:0xf bank_mask:0xf bound_ctrl:1
	v_add_f32_dpp v146, v146, v146 row_half_mirror row_mask:0xf bank_mask:0xf bound_ctrl:1
	v_add_f32_dpp v147, v147, v147 row_half_mirror row_mask:0xf bank_mask:0xf bound_ctrl:1
	v_add_f32_dpp v150, v150, v150 row_half_mirror row_mask:0xf bank_mask:0xf bound_ctrl:1
	v_add_f32_dpp v151, v151, v151 row_half_mirror row_mask:0xf bank_mask:0xf bound_ctrl:1
	v_add_f32_dpp v146, v146, v146 row_mirror row_mask:0xf bank_mask:0xf bound_ctrl:1
	v_add_f32_dpp v147, v147, v147 row_mirror row_mask:0xf bank_mask:0xf bound_ctrl:1
	v_add_f32_dpp v150, v150, v150 row_mirror row_mask:0xf bank_mask:0xf bound_ctrl:1
	v_add_f32_dpp v151, v151, v151 row_mirror row_mask:0xf bank_mask:0xf bound_ctrl:1
	v_readlane_b32 s44, v146, 16
	v_readlane_b32 s45, v146, 48
	v_readlane_b32 s46, v147, 16
	v_readlane_b32 s47, v147, 48
	v_readlane_b32 s0, v146, 0
	v_readlane_b32 s1, v146, 32
	v_readlane_b32 s2, v147, 0
	v_readlane_b32 s3, v147, 32
	v_readlane_b32 s4, v150, 0
	v_readlane_b32 s48, v150, 16
	v_readlane_b32 s5, v150, 32
	v_readlane_b32 s49, v150, 48
	v_readlane_b32 s42, v151, 0
	v_readlane_b32 s50, v151, 16
	v_readlane_b32 s43, v151, 32
	v_readlane_b32 s51, v151, 48
	v_mov_b32_e32 v146, s44
	v_mov_b32_e32 v147, s45
	v_mov_b32_e32 v150, s46
	v_mov_b32_e32 v151, s47
	v_mov_b32_e32 v152, s48
	v_mov_b32_e32 v153, s49
	v_mov_b32_e32 v154, s50
	v_mov_b32_e32 v155, s51
	v_pk_add_f32 v[146:147], s[0:1], v[146:147]
	v_pk_add_f32 v[150:151], s[2:3], v[150:151]
	v_pk_add_f32 v[152:153], s[4:5], v[152:153]
	v_pk_add_f32 v[154:155], s[42:43], v[154:155]
	v_mov_b32_e32 v156, v150
	v_mov_b32_e32 v157, v146
	v_mov_b32_e32 v146, v151
	v_mov_b32_e32 v150, v154
	v_mov_b32_e32 v151, v152
	v_mov_b32_e32 v152, v155
	v_pk_add_f32 v[146:147], v[156:157], v[146:147]
	v_pk_add_f32 v[150:151], v[150:151], v[152:153]
	v_pk_fma_f32 v[146:147], v[146:147], s[20:21], v[144:145] op_sel_hi:[1,0,0]
	v_pk_fma_f32 v[144:145], v[150:151], s[20:21], v[144:145] op_sel_hi:[1,0,0]
	v_mul_f32_e32 v150, 0x4b800000, v147
	v_cmp_gt_f32_e64 s[4:5], s39, v147
	v_mul_f32_e32 v151, 0x4b800000, v146
	v_cmp_gt_f32_e32 vcc, s39, v146
	v_mul_f32_e32 v152, 0x4b800000, v145
	v_mul_f32_e32 v153, 0x4b800000, v144
	v_cmp_gt_f32_e64 s[0:1], s39, v144
	v_cmp_gt_f32_e64 s[2:3], s39, v145
	v_cndmask_b32_e64 v147, v147, v150, s[4:5]
	v_cndmask_b32_e32 v146, v146, v151, vcc
	v_cndmask_b32_e64 v145, v145, v152, s[2:3]
	v_cndmask_b32_e64 v144, v144, v153, s[0:1]
	v_rsq_f32_e32 v147, v147
	v_rsq_f32_e32 v146, v146
	v_rsq_f32_e32 v145, v145
	v_rsq_f32_e32 v144, v144
	v_mul_f32_e32 v150, 0x45800000, v147
	v_mul_f32_e32 v151, 0x45800000, v146
	v_mul_f32_e32 v152, 0x45800000, v145
	v_mul_f32_e32 v153, 0x45800000, v144
	v_cndmask_b32_e64 v147, v147, v150, s[4:5]
	v_cndmask_b32_e32 v146, v146, v151, vcc
	v_cndmask_b32_e64 v145, v145, v152, s[2:3]
	v_cndmask_b32_e64 v144, v144, v153, s[0:1]
	v_mul_f32_e32 v139, v139, v147
	v_mul_f32_e32 v146, v158, v146
	v_mul_f32_e32 v145, v162, v145
	v_mul_f32_e32 v144, v168, v144
	s_waitcnt lgkmcnt(0)
	v_fmac_f32_e32 v182, v178, v139
	v_fmac_f32_e32 v183, v179, v146
	v_fmac_f32_e32 v184, v180, v145
	v_fmac_f32_e32 v185, v181, v144
	v_fmac_f32_e32 v182, v141, v143
	v_fmac_f32_e32 v183, v159, v160
	v_fmac_f32_e32 v184, v163, v164
	v_fmac_f32_e32 v185, v169, v170
	v_mul_f32_e32 v139, v182, v149
	v_mul_f32_e32 v141, v183, v161
	v_mul_f32_e32 v143, v184, v165
	v_mul_f32_e32 v144, v185, v171
	v_bfe_u32 v145, v139, 16, 1
	v_bfe_u32 v146, v141, 16, 1
	v_bfe_u32 v147, v143, 16, 1
	v_bfe_u32 v149, v144, 16, 1
	v_add3_u32 v139, v139, v145, s40
	v_add3_u32 v141, v141, v146, s40
	v_add3_u32 v143, v143, v147, s40
	v_add3_u32 v144, v144, v149, s40
	global_store_short_d16_hi v[166:167], v139, off offset:512
	global_store_short_d16_hi v[166:167], v141, off offset:640
	global_store_short_d16_hi v[166:167], v143, off offset:768
	global_store_short_d16_hi v[166:167], v144, off offset:896
	s_mov_b64 exec, s[52:53]
	s_nop 4
	s_andn2_b64 exec, exec, s[26:27]
	s_cbranch_execnz .LBB0_1748
	s_branch .LBB0_1743
